# grid barrier: per-XCC arrival atomic issued first, the LDS census words are read while it is in flight
# speedup vs baseline: 1.0025x; 1.0025x over previous
.LBB0_1500:
	v_readlane_b32 s2, v253, 48
	v_readlane_b32 s22, v254, 14
	s_cmp_lg_u32 s2, 0
	v_readlane_b32 s23, v254, 15
	v_readlane_b32 s20, v254, 16
	v_readlane_b32 s21, v254, 17
	s_cbranch_scc0 .LBB0_1669
	s_waitcnt vmcnt(0) lgkmcnt(0)
	s_waitcnt vmcnt(0)
	s_barrier
	s_mov_b64 s[4:5], exec
	v_readlane_b32 s8, v251, 2
	v_readlane_b32 s9, v251, 3
	s_and_b64 s[8:9], s[4:5], s[8:9]
	s_mov_b64 exec, s[8:9]
	s_cbranch_execz .LBB0_1526
	s_getreg_b32 s2, hwreg(HW_REG_XCC_ID, 0, 4)
	s_and_b32 s2, s2, 15
	s_lshl_b32 s12, s2, 8
	v_readlane_b32 s14, v251, 0
	v_readlane_b32 s15, v251, 1
	v_mov_b32_e32 v6, 1
	v_mov_b32_e32 v7, 0x1000
	s_add_u32 s14, s14, s12
	s_addc_u32 s15, s15, 0
	s_nop 1
	global_atomic_add v6, v7, v6, s[14:15] offset:1024 sc0
	s_add_i32 s10, 0, 0x20000
	s_mov_b64 s[8:9], src_shared_base
	s_cmp_lg_u32 s10, -1
	s_cselect_b32 s8, s10, 0
	s_cselect_b32 s11, s9, 0
	s_add_i32 s12, 0, 0x20004
	s_cmp_lg_u32 s12, -1
	v_mov_b32_e32 v0, s8
	v_mov_b32_e32 v1, s11
	s_cselect_b32 s8, s12, 0
	s_cselect_b32 s9, s9, 0
	flat_load_dword v2, v[0:1] sc0 sc1
	s_waitcnt vmcnt(0)
	v_mov_b32_e32 v0, s8
	v_mov_b32_e32 v1, s9
	flat_load_dword v0, v[0:1] sc0 sc1
	s_waitcnt vmcnt(0) lgkmcnt(0)
	v_cmp_eq_u32_e32 vcc, 0, v2
	s_and_saveexec_b64 s[8:9], vcc
	s_cbranch_execz .LBB0_1504
	v_readlane_b32 s14, v252, 55
	v_readlane_b32 s15, v252, 56
	s_cmp_eq_u32 s2, 0
	s_nop 3
	global_load_dword v0, v153, s[14:15] sc1
	v_readlane_b32 s14, v252, 57
	v_readlane_b32 s15, v252, 58
	s_waitcnt vmcnt(0)
	v_cmp_ne_u32_e32 vcc, 0, v0
	s_nop 2
	global_load_dword v2, v153, s[14:15] sc1
	v_cndmask_b32_e64 v1, 0, 1, vcc
	s_cselect_b64 vcc, -1, 0
	v_cndmask_b32_e32 v0, 0, v0, vcc
	s_cmp_eq_u32 s2, 1
	v_readlane_b32 s14, v252, 59
	v_readlane_b32 s15, v252, 60
	s_waitcnt vmcnt(0)
	v_cmp_ne_u32_e32 vcc, 0, v2
	s_nop 1
	v_addc_co_u32_e32 v1, vcc, 0, v1, vcc
	s_cselect_b64 vcc, -1, 0
	s_nop 0
	v_cndmask_b32_e32 v0, v0, v2, vcc
	global_load_dword v2, v153, s[14:15] sc1
	s_cmp_eq_u32 s2, 2
	v_readlane_b32 s14, v252, 61
	v_readlane_b32 s15, v252, 62
	s_waitcnt vmcnt(0)
	v_cmp_ne_u32_e32 vcc, 0, v2
	s_nop 1
	v_cndmask_b32_e64 v3, 0, 1, vcc
	s_cselect_b64 vcc, -1, 0
	v_cndmask_b32_e32 v0, v0, v2, vcc
	global_load_dword v2, v153, s[14:15] sc1
	s_cmp_eq_u32 s2, 3
	v_readlane_b32 s14, v252, 63
	v_readlane_b32 s15, v253, 0
	s_waitcnt vmcnt(0)
	v_cmp_ne_u32_e32 vcc, 0, v2
	s_nop 1
	v_addc_co_u32_e32 v1, vcc, v1, v3, vcc
	s_cselect_b64 vcc, -1, 0
	s_nop 0
	v_cndmask_b32_e32 v0, v0, v2, vcc
	global_load_dword v2, v153, s[14:15] sc1
	s_cmp_eq_u32 s2, 4
	v_readlane_b32 s14, v253, 1
	v_readlane_b32 s15, v253, 2
	s_waitcnt vmcnt(0)
	v_cmp_ne_u32_e32 vcc, 0, v2
	s_nop 1
	v_cndmask_b32_e64 v3, 0, 1, vcc
	s_cselect_b64 vcc, -1, 0
	v_cndmask_b32_e32 v0, v0, v2, vcc
	global_load_dword v2, v153, s[14:15] sc1
	s_cmp_eq_u32 s2, 5
	v_readlane_b32 s14, v253, 3
	v_readlane_b32 s15, v253, 4
	s_waitcnt vmcnt(0)
	v_cmp_ne_u32_e32 vcc, 0, v2
	s_nop 1
	v_addc_co_u32_e32 v1, vcc, v1, v3, vcc
	s_cselect_b64 vcc, -1, 0
	s_nop 0
	v_cndmask_b32_e32 v0, v0, v2, vcc
	global_load_dword v2, v153, s[14:15] sc1
	s_cmp_eq_u32 s2, 6
	v_readlane_b32 s14, v253, 5
	v_readlane_b32 s15, v253, 6
	s_waitcnt vmcnt(0)
	v_cmp_ne_u32_e32 vcc, 0, v2
	s_nop 1
	v_cndmask_b32_e64 v3, 0, 1, vcc
	s_cselect_b64 vcc, -1, 0
	v_cndmask_b32_e32 v0, v0, v2, vcc
	global_load_dword v2, v153, s[14:15] sc1
	s_cmp_eq_u32 s2, 7
	v_readlane_b32 s14, v253, 7
	v_readlane_b32 s15, v253, 8
	s_waitcnt vmcnt(0)
	v_cmp_ne_u32_e32 vcc, 0, v2
	s_nop 1
	v_addc_co_u32_e32 v1, vcc, v1, v3, vcc
	s_cselect_b64 vcc, -1, 0
	s_nop 0
	v_cndmask_b32_e32 v0, v0, v2, vcc
	global_load_dword v2, v153, s[14:15] sc1
	s_cmp_eq_u32 s2, 8
	v_readlane_b32 s14, v253, 9
	v_readlane_b32 s15, v253, 10
	s_waitcnt vmcnt(0)
	v_cmp_ne_u32_e32 vcc, 0, v2
	s_nop 1
	v_cndmask_b32_e64 v3, 0, 1, vcc
	s_cselect_b64 vcc, -1, 0
	v_cndmask_b32_e32 v0, v0, v2, vcc
	global_load_dword v2, v153, s[14:15] sc1
	s_cmp_eq_u32 s2, 9
	v_readlane_b32 s14, v253, 11
	v_readlane_b32 s15, v253, 12
	s_waitcnt vmcnt(0)
	v_cmp_ne_u32_e32 vcc, 0, v2
	s_nop 1
	v_addc_co_u32_e32 v1, vcc, v1, v3, vcc
	s_cselect_b64 vcc, -1, 0
	s_nop 0
	v_cndmask_b32_e32 v0, v0, v2, vcc
	global_load_dword v2, v153, s[14:15] sc1
	s_cmp_eq_u32 s2, 10
	v_readlane_b32 s14, v253, 13
	v_readlane_b32 s15, v253, 14
	s_waitcnt vmcnt(0)
	v_cmp_ne_u32_e32 vcc, 0, v2
	s_nop 1
	v_cndmask_b32_e64 v3, 0, 1, vcc
	s_cselect_b64 vcc, -1, 0
	v_cndmask_b32_e32 v0, v0, v2, vcc
	global_load_dword v2, v153, s[14:15] sc1
	s_cmp_eq_u32 s2, 11
	v_readlane_b32 s14, v253, 15
	v_readlane_b32 s15, v253, 16
	s_waitcnt vmcnt(0)
	v_cmp_ne_u32_e32 vcc, 0, v2
	s_nop 1
	v_addc_co_u32_e32 v1, vcc, v1, v3, vcc
	s_cselect_b64 vcc, -1, 0
	s_nop 0
	v_cndmask_b32_e32 v0, v0, v2, vcc
	global_load_dword v2, v153, s[14:15] sc1
	s_cmp_eq_u32 s2, 12
	v_readlane_b32 s14, v253, 17
	v_readlane_b32 s15, v253, 18
	s_waitcnt vmcnt(0)
	v_cmp_ne_u32_e32 vcc, 0, v2
	s_nop 1
	v_cndmask_b32_e64 v3, 0, 1, vcc
	s_cselect_b64 vcc, -1, 0
	v_cndmask_b32_e32 v0, v0, v2, vcc
	global_load_dword v2, v153, s[14:15] sc1
	s_cmp_eq_u32 s2, 13
	v_readlane_b32 s14, v253, 19
	v_readlane_b32 s15, v253, 20
	s_waitcnt vmcnt(0)
	v_cmp_ne_u32_e32 vcc, 0, v2
	s_nop 1
	v_addc_co_u32_e32 v1, vcc, v1, v3, vcc
	s_cselect_b64 vcc, -1, 0
	s_nop 0
	v_cndmask_b32_e32 v0, v0, v2, vcc
	global_load_dword v2, v153, s[14:15] sc1
	s_cmp_eq_u32 s2, 14
	v_readlane_b32 s14, v253, 21
	v_readlane_b32 s15, v253, 22
	s_waitcnt vmcnt(0)
	v_cmp_ne_u32_e32 vcc, 0, v2
	s_nop 1
	v_cndmask_b32_e64 v3, 0, 1, vcc
	s_cselect_b64 vcc, -1, 0
	v_cndmask_b32_e32 v0, v0, v2, vcc
	global_load_dword v2, v153, s[14:15] sc1
	s_cmp_eq_u32 s2, 15
	s_waitcnt vmcnt(0)
	v_cmp_ne_u32_e32 vcc, 0, v2
	s_nop 1
	v_addc_co_u32_e32 v1, vcc, v1, v3, vcc
	s_cselect_b64 vcc, -1, 0
	s_cmp_lg_u32 s10, -1
	s_cselect_b32 s13, s10, 0
	s_mov_b64 s[10:11], src_shared_base
	v_cndmask_b32_e32 v0, v0, v2, vcc
	s_cselect_b32 s10, s11, 0
	s_cmp_lg_u32 s12, -1
	v_max_u32_e32 v2, 1, v0
	v_mov_b32_e32 v4, s13
	v_mov_b32_e32 v5, s10
	s_cselect_b32 s10, s12, 0
	s_cselect_b32 s11, s11, 0
	v_max_u32_e32 v0, 1, v1
	flat_store_dword v[4:5], v2 sc0 sc1
	s_waitcnt vmcnt(0)
	v_mov_b32_e32 v4, s10
	v_mov_b32_e32 v5, s11
	flat_store_dword v[4:5], v0 sc0 sc1
	s_waitcnt vmcnt(0)
.LBB0_1504:
	s_or_b64 exec, exec, s[8:9]
	s_mov_b64 s[10:11], exec
	s_lshl_b32 s2, s2, 8
	v_readlane_b32 s8, v251, 0
	v_mbcnt_lo_u32_b32 v1, s10, 0
	v_readlane_b32 s9, v251, 1
	s_add_u32 s8, s8, s2
	v_mbcnt_hi_u32_b32 v1, s11, v1
	s_addc_u32 s9, s9, 0
	v_cmp_eq_u32_e32 vcc, 0, v1
	s_and_saveexec_b64 s[12:13], vcc
	s_cbranch_execz .LBB0_1506
	s_waitcnt vmcnt(0)
	v_mov_b32_e32 v3, v6
